# mixer queue: static first unit, XCD-clustered ids (32*(bid&7)+(bid>>3)); later fetches counter + grid size
# baseline (speedup 1.0000x reference)
.LBB0_413:
	v_mov_b32_e32 v130, v220
	s_nop 0
	v_cmp_eq_u32_e32 vcc, 0, v130
	s_barrier
	s_and_saveexec_b64 s[0:1], vcc
	s_cbranch_execz .LBB0_417
	s_mov_b64 s[4:5], exec
	v_mbcnt_lo_u32_b32 v1, s4, 0
	v_mbcnt_hi_u32_b32 v1, s5, v1
	v_cmp_eq_u32_e32 vcc, 0, v1
	s_and_saveexec_b64 s[2:3], vcc
	s_cbranch_execz .LBB0_416
	s_cmp_eq_u32 s101, 1
	s_cbranch_scc0 .Lsq_dyn
	s_mov_b32 s101, 0
	v_readlane_b32 s4, v252, 8
	v_readlane_b32 s5, v253, 6
	s_nop 0
	s_cmp_eq_u32 s5, 0x100
	s_cbranch_scc0 .Lsq_lin
	s_and_b32 s5, s4, 7
	s_lshl_b32 s5, s5, 5
	s_lshr_b32 s4, s4, 3
	s_add_u32 s4, s4, s5
.Lsq_lin:
	v_mov_b32_e32 v2, s4
	s_branch .LBB0_416
